# all attention waves on the non-shifted loop; softmax exp/cvt/sum of row group c+1 interleaved under P.V MFMAs of group c
# speedup vs baseline: 1.0239x; 1.0128x over previous
; #define LAS __attribute__((address_space(3)))
; #define ATT_BAR() asm volatile("s_waitcnt lgkmcnt(0)\n\ts_barrier" ::: "memory")
; #define ATT_BAR() asm volatile("s_waitcnt vmcnt(0) lgkmcnt(0)\n\ts_barrier" ::: "memory")
; template <int DQK>
; __device__ __forceinline__ void attn_pass4(LAS unsigned char* lds, const bf16* Qp, int qpitch, const bf16* Kp, int kpitch, const bf16* Vp, int vpitch, int q0, f32x16 (&o)[4], float (&rl)[16]) {
;     ...
;     int tid = threadIdx.x; asm volatile("" : "+v"(tid));
;     const int lane = tid & 63, r32 = lane & 31, hi = lane >> 5;
;     const int wid = __builtin_amdgcn_readfirstlane(tid >> 6);
;     const bool shifted = wid >= 4;
;     LAS float* wsf = (LAS float*)(lds + G::WS_OFF) + wid * 64;
;     bf16x8 qf[DQK / 16];
;     { const bf16* qrow = Qp + (size_t)(q0 + wid * 32 + r32) * qpitch + 8 * hi;
; #pragma unroll
;       for (int d0 = 0; d0 < DQK / 16; ++d0) qf[d0] = *(const bf16x8*)(qrow + 16 * d0); }
;     const int NT = (q0 + 256) / 64;
;     const int qw0 = q0 + wid * 32;
;     const unsigned lds0 = (unsigned)(size_t)lds;
;     constexpr int KS = G::KP / 16, KD = DQK / 8, KJ = (KS + 7) / 8, VS = VP / 16, VD = 16, VJ = (VS + 7) / 8;
;     unsigned koff[KJ], voff[VJ];
; #pragma unroll
;     for (int j = 0; j < KJ; ++j) { const int sidx = (j * 8 + wid) * 64 + lane, row = (sidx / KS) & 63, c = sidx % KS; koff[j] = (unsigned)(row * kpitch + (c < KD ? c : KD - 1) * 8) * 2u; }
; #pragma unroll
;     for (int j = 0; j < VJ; ++j) { const int sidx = (j * 8 + wid) * 64 + lane, row = (sidx / VS) & 63, c = sidx % VS; voff[j] = (unsigned)(row * vpitch + (c < VD ? c : VD - 1) * 8) * 2u; }
;     ...
; #pragma unroll
;     for (int db = 0; db < 4; ++db)
; #pragma unroll
;         for (int r = 0; r < 16; ++r) o[db][r] = 0.f;
;     float mhat = 0.f, l = 0.f;
;     f32x16 negm;
; #pragma unroll
;     for (int r = 0; r < 16; ++r) negm[r] = 0.f;
;     ...
;     ATT_DMA(0, 0, 0); ATT_BAR();
;     int vcur = 0;
;     ...
;     if (!shifted) {
.LBB0_619:
	s_andn2_b32 s5, s5, 63
	s_lshl_b32 s5, s5, 2
	s_add_i32 s8, s30, 0x100
	s_add_i32 s81, s5, 0
	s_waitcnt vmcnt(0) lgkmcnt(0)
	s_barrier
	v_and_b32_e32 v167, 63, v32
	s_add_i32 s81, s81, 0x13800
	s_lshr_b32 s31, s8, 6
	v_mul_u32_u24_e32 v35, 0x90, v34
	v_lshlrev_b32_e32 v36, 1, v32
	v_lshlrev_b32_e32 v37, 3, v32
	s_cmp_lt_i32 s3, 8
	s_mov_b64 s[70:71], -1
	v_cmp_gt_u32_e64 s[8:9], 32, v167
	v_add3_u32 v188, 0, v35, v168
	v_lshlrev_b32_e32 v190, 2, v180
	v_lshl_add_u32 v169, v34, 2, s81
	v_lshrrev_b32_e32 v192, 2, v32
	v_and_b32_e32 v184, 32, v36
	v_and_b32_e32 v186, 24, v37
	s_cbranch_scc0 .LBB0_642
	v_and_or_b32 v32, v192, 3, v190
	v_mad_u32_u24 v32, v32, s82, 0
	v_mov_b32_e32 v46, v33
	v_mov_b32_e32 v47, v33
	v_add3_u32 v194, v32, v184, v186
	v_mov_b32_e32 v32, v33
	v_mov_b32_e32 v34, v33
	v_mov_b32_e32 v35, v33
	v_mov_b32_e32 v36, v33
	v_mov_b32_e32 v37, v33
	v_mov_b32_e32 v38, v33
	v_mov_b32_e32 v39, v33
	v_mov_b32_e32 v40, v33
	v_mov_b32_e32 v41, v33
	v_mov_b32_e32 v42, v33
	v_mov_b32_e32 v43, v33
	v_mov_b32_e32 v44, v33
	v_mov_b32_e32 v45, v33
	v_mov_b64_e32 v[96:97], v[46:47]
	v_mov_b64_e32 v[80:81], v[46:47]
	v_mov_b64_e32 v[64:65], v[46:47]
	s_lshl_b32 s5, s3, 10
	v_mov_b32_e32 v196, 0
	v_mov_b64_e32 v[94:95], v[44:45]
	v_mov_b64_e32 v[92:93], v[42:43]
	v_mov_b64_e32 v[90:91], v[40:41]
	v_mov_b64_e32 v[88:89], v[38:39]
	v_mov_b64_e32 v[86:87], v[36:37]
	v_mov_b64_e32 v[84:85], v[34:35]
	v_mov_b64_e32 v[82:83], v[32:33]
	v_mov_b64_e32 v[78:79], v[44:45]
	v_mov_b64_e32 v[76:77], v[42:43]
	v_mov_b64_e32 v[74:75], v[40:41]
	v_mov_b64_e32 v[72:73], v[38:39]
	v_mov_b64_e32 v[70:71], v[36:37]
	v_mov_b64_e32 v[68:69], v[34:35]
	v_mov_b64_e32 v[66:67], v[32:33]
	v_mov_b64_e32 v[62:63], v[44:45]
	v_mov_b64_e32 v[60:61], v[42:43]
	v_mov_b64_e32 v[58:59], v[40:41]
	v_mov_b64_e32 v[56:57], v[38:39]
	v_mov_b64_e32 v[54:55], v[36:37]
	v_mov_b64_e32 v[52:53], v[34:35]
	v_mov_b64_e32 v[50:51], v[32:33]
	v_mov_b64_e32 v[48:49], v[46:47]
	s_add_i32 s26, s5, 0x4800
	s_or_b32 s27, s76, 31
	v_mov_b32_e32 v171, v33
	v_mov_b32_e32 v177, v33
	s_lshl_b32 s80, s2, 10
	v_mov_b32_e32 v173, v33
	v_mov_b32_e32 v175, v33
	v_mov_b32_e32 v179, v33
	s_mov_b32 s24, 0
	s_mov_b32 s18, 63
	s_mov_b64 s[70:71], s[60:61]
	v_mov_b64_e32 v[46:47], v[44:45]
	v_mov_b64_e32 v[44:45], v[42:43]
	v_mov_b64_e32 v[42:43], v[40:41]
	v_mov_b64_e32 v[40:41], v[38:39]
	v_mov_b64_e32 v[38:39], v[36:37]
	v_mov_b64_e32 v[36:37], v[34:35]
	v_mov_b64_e32 v[34:35], v[32:33]
	v_mov_b32_e32 v182, 0
	s_mov_b32 s72, 0
	v_mov_b32_e32 v98, 0
	v_mov_b32_e32 v99, v196
	v_mov_b32_e32 v100, v196
	v_mov_b32_e32 v101, v196
	v_mov_b32_e32 v102, v196
	v_mov_b32_e32 v103, v196
	v_mov_b32_e32 v104, v196
	v_mov_b32_e32 v105, v196
	v_mov_b32_e32 v106, v196
	v_mov_b32_e32 v107, v196
	v_mov_b32_e32 v108, v196
	v_mov_b32_e32 v109, v196
	v_mov_b32_e32 v110, v196
	v_mov_b32_e32 v111, v196
	v_mov_b32_e32 v112, v196
	v_mov_b32_e32 v113, v196

.LBB0_624:
	s_add_u32 s74, s70, 0x4000000
	s_mul_i32 s73, s35, 0x5000
	s_addc_u32 s75, s71, 0
	s_add_i32 s73, s26, s73
	v_lshl_add_u64 v[114:115], s[74:75], 0, v[172:173]
	s_add_i32 s73, s73, 0
	s_mov_b32 vcc_lo, m0
	s_mov_b32 m0, s73
	s_nop 0
	global_load_lds_dwordx4 v[114:115], off
	s_mov_b32 m0, vcc_lo
	s_add_i32 vcc_lo, s73, 0x2000
	v_lshl_add_u64 v[114:115], s[74:75], 0, v[174:175]
	s_mov_b32 vcc_hi, m0
	s_mov_b32 m0, vcc_lo
	s_nop 0
	global_load_lds_dwordx4 v[114:115], off
	s_mov_b32 m0, vcc_hi
	v_readfirstlane_b32 s32, v242
	s_cmpk_gt_u32 s32, 0xff
	s_cbranch_scc1 .Lskip_v2_0
	v_lshl_add_u64 v[114:115], s[74:75], 0, v[178:179]
	s_addk_i32 s73, 0x4000
	s_mov_b32 s74, m0
	s_mov_b32 m0, s73
	s_nop 0
	global_load_lds_dwordx4 v[114:115], off
	s_mov_b32 m0, s74
.Lskip_v2_0:
.LBB0_625:
	s_sub_i32 s73, s18, 63
	s_cmp_gt_i32 s73, s27
	s_cbranch_scc1 .LBB0_638
	s_bitcmp1_b32 s72, 0
	s_cselect_b32 s72, 0x2400, 0
	v_add_u32_e32 v32, s72, v188
	s_setprio 1
	ds_read_b128 v[214:217], v32
	ds_read_b128 v[218:221], v32 offset:4608
	ds_read_b128 v[222:225], v32 offset:32
	ds_read_b128 v[226:229], v32 offset:4640
	ds_read_b128 v[230:233], v32 offset:64
	ds_read_b128 v[234:237], v32 offset:4672
	ds_read_b128 v[238:241], v32 offset:96
	ds_read_b128 v[244:247], v32 offset:4704
	s_waitcnt lgkmcnt(7)
	v_mfma_f32_32x32x16_bf16 v[114:129], v[214:217], v[146:149], v[98:113]
	s_waitcnt lgkmcnt(6)
	v_mfma_f32_32x32x16_bf16 v[130:145], v[218:221], v[146:149], v[98:113]
	s_waitcnt lgkmcnt(5)
	v_mfma_f32_32x32x16_bf16 v[114:129], v[222:225], v[150:153], v[114:129]
	s_waitcnt lgkmcnt(4)
	v_mfma_f32_32x32x16_bf16 v[130:145], v[226:229], v[150:153], v[130:145]
	s_waitcnt lgkmcnt(3)
	v_mfma_f32_32x32x16_bf16 v[114:129], v[230:233], v[154:157], v[114:129]
	s_waitcnt lgkmcnt(2)
	v_mfma_f32_32x32x16_bf16 v[130:145], v[234:237], v[154:157], v[130:145]
	s_waitcnt lgkmcnt(1)
	v_mfma_f32_32x32x16_bf16 v[114:129], v[238:241], v[158:161], v[114:129]
	s_waitcnt lgkmcnt(0)
	v_mfma_f32_32x32x16_bf16 v[130:145], v[244:247], v[158:161], v[130:145]
	s_setprio 0
	s_cmp_le_i32 s18, s76
	s_cbranch_scc1 .LBB0_628
	v_add_u32_e32 v32, s18, v190
	v_subrev_u32_e32 v200, 31, v32
	v_subrev_u32_e32 v198, 63, v32
	v_cmp_le_i32_e32 vcc, v200, v166
	s_nop 4
	v_cndmask_b32_e32 v130, v208, v130, vcc
	v_cmp_lt_i32_e32 vcc, v198, v166
	s_nop 1
	v_cndmask_b32_e32 v115, v208, v115, vcc
	v_cmp_le_i32_e32 vcc, v198, v166
	v_subrev_u32_e32 v198, 30, v32
	s_nop 0
	v_cndmask_b32_e32 v114, v208, v114, vcc
	v_cmp_le_i32_e32 vcc, v198, v166
	v_subrev_u32_e32 v198, 61, v32
	s_nop 0
	v_cndmask_b32_e32 v131, v208, v131, vcc
	v_cmp_le_i32_e32 vcc, v198, v166
	v_subrev_u32_e32 v198, 29, v32
	s_nop 0
	v_cndmask_b32_e32 v116, v208, v116, vcc
	v_cmp_le_i32_e32 vcc, v198, v166
	v_subrev_u32_e32 v198, 60, v32
	s_nop 0
	v_cndmask_b32_e32 v132, v208, v132, vcc
	v_cmp_le_i32_e32 vcc, v198, v166
	v_subrev_u32_e32 v198, 28, v32
	s_nop 0
	v_cndmask_b32_e32 v117, v208, v117, vcc
	v_cmp_le_i32_e32 vcc, v198, v166
	v_subrev_u32_e32 v198, 55, v32
	s_nop 0
	v_cndmask_b32_e32 v133, v208, v133, vcc
	v_cmp_le_i32_e32 vcc, v198, v166
	v_subrev_u32_e32 v198, 23, v32
	s_nop 0
	v_cndmask_b32_e32 v118, v208, v118, vcc
	v_cmp_le_i32_e32 vcc, v198, v166
	v_subrev_u32_e32 v198, 54, v32
	s_nop 0
	v_cndmask_b32_e32 v134, v208, v134, vcc
	v_cmp_le_i32_e32 vcc, v198, v166
	v_subrev_u32_e32 v198, 22, v32
	s_nop 0
	v_cndmask_b32_e32 v119, v208, v119, vcc
	v_cmp_le_i32_e32 vcc, v198, v166
	v_subrev_u32_e32 v198, 53, v32
	s_nop 0
	v_cndmask_b32_e32 v135, v208, v135, vcc
	v_cmp_le_i32_e32 vcc, v198, v166
	v_subrev_u32_e32 v198, 21, v32
	s_nop 0
	v_cndmask_b32_e32 v120, v208, v120, vcc
	v_cmp_le_i32_e32 vcc, v198, v166
	v_subrev_u32_e32 v198, 52, v32
	s_nop 0
	v_cndmask_b32_e32 v136, v208, v136, vcc
	v_cmp_le_i32_e32 vcc, v198, v166
	v_subrev_u32_e32 v198, 20, v32
	s_nop 0
	v_cndmask_b32_e32 v121, v208, v121, vcc
	v_cmp_le_i32_e32 vcc, v198, v166
	v_subrev_u32_e32 v198, 47, v32
	s_nop 0
	v_cndmask_b32_e32 v137, v208, v137, vcc
	v_cmp_le_i32_e32 vcc, v198, v166
	v_add_u32_e32 v198, -15, v32
	s_nop 0
	v_cndmask_b32_e32 v122, v208, v122, vcc
	v_cmp_le_i32_e32 vcc, v198, v166
	v_subrev_u32_e32 v198, 46, v32
	s_nop 0
	v_cndmask_b32_e32 v138, v208, v138, vcc
	v_cmp_le_i32_e32 vcc, v198, v166
	v_add_u32_e32 v198, -14, v32
	s_nop 0
	v_cndmask_b32_e32 v123, v208, v123, vcc
	v_cmp_le_i32_e32 vcc, v198, v166
	v_subrev_u32_e32 v198, 45, v32
	s_nop 0
	v_cndmask_b32_e32 v139, v208, v139, vcc
	v_cmp_le_i32_e32 vcc, v198, v166
	v_add_u32_e32 v198, -13, v32
	s_nop 0
	v_cndmask_b32_e32 v124, v208, v124, vcc
	v_cmp_le_i32_e32 vcc, v198, v166
	v_subrev_u32_e32 v198, 44, v32
	s_nop 0
	v_cndmask_b32_e32 v140, v208, v140, vcc
	v_cmp_le_i32_e32 vcc, v198, v166
	v_add_u32_e32 v198, -12, v32
	s_nop 0
	v_cndmask_b32_e32 v125, v208, v125, vcc
	v_cmp_le_i32_e32 vcc, v198, v166
	v_subrev_u32_e32 v198, 39, v32
	s_nop 0
	v_cndmask_b32_e32 v141, v208, v141, vcc
	v_cmp_le_i32_e32 vcc, v198, v166
	v_add_u32_e32 v198, -7, v32
	s_nop 0
	v_cndmask_b32_e32 v126, v208, v126, vcc
	v_cmp_le_i32_e32 vcc, v198, v166
	v_subrev_u32_e32 v198, 38, v32
	s_nop 0
	v_cndmask_b32_e32 v142, v208, v142, vcc
	v_cmp_le_i32_e32 vcc, v198, v166
	v_add_u32_e32 v198, -6, v32
	s_nop 0
	v_cndmask_b32_e32 v127, v208, v127, vcc
	v_cmp_le_i32_e32 vcc, v198, v166
	v_subrev_u32_e32 v198, 37, v32
	s_nop 0
	v_cndmask_b32_e32 v143, v208, v143, vcc
	v_cmp_le_i32_e32 vcc, v198, v166
	v_add_u32_e32 v198, -5, v32
	s_nop 0
	v_cndmask_b32_e32 v128, v208, v128, vcc
	v_cmp_le_i32_e32 vcc, v198, v166
	v_subrev_u32_e32 v198, 36, v32
	v_add_u32_e32 v32, -4, v32
	v_cndmask_b32_e32 v144, v208, v144, vcc
	v_cmp_le_i32_e32 vcc, v198, v166
	s_nop 1
	v_cndmask_b32_e32 v129, v208, v129, vcc
	v_cmp_le_i32_e32 vcc, v32, v166
	s_nop 1
	v_cndmask_b32_e32 v145, v208, v145, vcc

.LBB0_637:
	s_mulk_i32 s24, 0x5000
	v_add_u32_e32 v32, s24, v194
	s_setprio 1
	ds_read_b64_tr_b16 v[214:215], v32 offset:18432
	ds_read_b64_tr_b16 v[216:217], v32 offset:20992
	ds_read_b64_tr_b16 v[218:219], v32 offset:18496
	ds_read_b64_tr_b16 v[220:221], v32 offset:21056
	ds_read_b64_tr_b16 v[222:223], v32 offset:18560
	ds_read_b64_tr_b16 v[224:225], v32 offset:21120
	ds_read_b64_tr_b16 v[226:227], v32 offset:18624
	ds_read_b64_tr_b16 v[228:229], v32 offset:21184
	ds_read_b64_tr_b16 v[230:231], v32 offset:23552
	ds_read_b64_tr_b16 v[232:233], v32 offset:26112
	v_exp_f32_e32 v114, v114
	v_exp_f32_e32 v115, v115
	v_exp_f32_e32 v116, v116
	v_exp_f32_e32 v117, v117
	v_exp_f32_e32 v118, v118
	v_cvt_pk_bf16_f32 v234, v114, v115
	v_exp_f32_e32 v119, v119
	v_cvt_pk_bf16_f32 v235, v116, v117
	v_exp_f32_e32 v120, v120
	v_exp_f32_e32 v121, v121
	v_cvt_pk_bf16_f32 v236, v118, v119
	s_nop 0
	v_cvt_pk_bf16_f32 v237, v120, v121
	s_nop 1
	s_waitcnt lgkmcnt(8)
	v_mfma_f32_32x32x16_bf16 v[82:97], v[234:237], v[214:217], v[82:97]
	ds_read_b64_tr_b16 v[214:215], v32 offset:23616
	ds_read_b64_tr_b16 v[216:217], v32 offset:26176
	v_exp_f32_e32 v122, v122
	v_exp_f32_e32 v123, v123
	v_exp_f32_e32 v124, v124
	s_waitcnt lgkmcnt(8)
	v_mfma_f32_32x32x16_bf16 v[66:81], v[234:237], v[218:221], v[66:81]
	ds_read_b64_tr_b16 v[218:219], v32 offset:23680
	ds_read_b64_tr_b16 v[220:221], v32 offset:26240
	v_exp_f32_e32 v125, v125
	v_exp_f32_e32 v126, v126
	v_exp_f32_e32 v127, v127
	v_cvt_pk_bf16_f32 v238, v122, v123
	v_add_f32_e32 v252, v114, v115
	s_waitcnt lgkmcnt(8)
	v_mfma_f32_32x32x16_bf16 v[50:65], v[234:237], v[222:225], v[50:65]
	ds_read_b64_tr_b16 v[222:223], v32 offset:23744
	ds_read_b64_tr_b16 v[224:225], v32 offset:26304
	v_exp_f32_e32 v128, v128
	v_exp_f32_e32 v129, v129
	v_cvt_pk_bf16_f32 v239, v124, v125
	v_add_f32_e32 v253, v116, v117
	s_waitcnt lgkmcnt(8)
	v_mfma_f32_32x32x16_bf16 v[34:49], v[234:237], v[226:229], v[34:49]
	ds_read_b64_tr_b16 v[226:227], v32 offset:28672
	ds_read_b64_tr_b16 v[228:229], v32 offset:31232
	v_cvt_pk_bf16_f32 v240, v126, v127
	v_cvt_pk_bf16_f32 v241, v128, v129
	v_add_f32_e32 v254, v118, v119
	v_add_f32_e32 v213, v120, v121
	s_waitcnt lgkmcnt(8)
	v_mfma_f32_32x32x16_bf16 v[82:97], v[238:241], v[230:233], v[82:97]
	ds_read_b64_tr_b16 v[230:231], v32 offset:28736
	ds_read_b64_tr_b16 v[232:233], v32 offset:31296
	v_exp_f32_e32 v130, v130
	v_exp_f32_e32 v131, v131
	v_exp_f32_e32 v132, v132
	v_add_f32_e32 v252, v252, v122
	s_waitcnt lgkmcnt(8)
	v_mfma_f32_32x32x16_bf16 v[66:81], v[238:241], v[214:217], v[66:81]
	ds_read_b64_tr_b16 v[214:215], v32 offset:28800
	ds_read_b64_tr_b16 v[216:217], v32 offset:31360
	v_exp_f32_e32 v133, v133
	v_exp_f32_e32 v134, v134
	v_exp_f32_e32 v135, v135
	v_cvt_pk_bf16_f32 v244, v130, v131
	v_add_f32_e32 v253, v253, v123
	s_waitcnt lgkmcnt(8)
	v_mfma_f32_32x32x16_bf16 v[50:65], v[238:241], v[218:221], v[50:65]
	ds_read_b64_tr_b16 v[218:219], v32 offset:28864
	ds_read_b64_tr_b16 v[220:221], v32 offset:31424
	v_exp_f32_e32 v136, v136
	v_exp_f32_e32 v137, v137
	v_cvt_pk_bf16_f32 v245, v132, v133
	v_add_f32_e32 v254, v254, v124
	v_add_f32_e32 v213, v213, v125
	s_waitcnt lgkmcnt(8)
	v_mfma_f32_32x32x16_bf16 v[34:49], v[238:241], v[222:225], v[34:49]
	ds_read_b64_tr_b16 v[222:223], v32 offset:33792
	ds_read_b64_tr_b16 v[224:225], v32 offset:36352
	v_cvt_pk_bf16_f32 v246, v134, v135
	v_add_f32_e32 v252, v252, v126
	v_cvt_pk_bf16_f32 v247, v136, v137
	v_add_f32_e32 v253, v253, v127
	v_add_f32_e32 v254, v254, v128
	v_add_f32_e32 v213, v213, v129
	s_waitcnt lgkmcnt(8)
	v_mfma_f32_32x32x16_bf16 v[82:97], v[244:247], v[226:229], v[82:97]
	ds_read_b64_tr_b16 v[226:227], v32 offset:33856
	ds_read_b64_tr_b16 v[228:229], v32 offset:36416
	v_exp_f32_e32 v138, v138
	v_exp_f32_e32 v139, v139
	v_exp_f32_e32 v140, v140
	v_add_f32_e32 v252, v252, v130
	s_waitcnt lgkmcnt(8)
	v_mfma_f32_32x32x16_bf16 v[66:81], v[244:247], v[230:233], v[66:81]
	ds_read_b64_tr_b16 v[230:231], v32 offset:33920
	ds_read_b64_tr_b16 v[232:233], v32 offset:36480
	v_exp_f32_e32 v141, v141
	v_exp_f32_e32 v142, v142
	v_exp_f32_e32 v143, v143
	v_cvt_pk_bf16_f32 v248, v138, v139
	v_add_f32_e32 v253, v253, v131
	s_waitcnt lgkmcnt(8)
	v_mfma_f32_32x32x16_bf16 v[50:65], v[244:247], v[214:217], v[50:65]
	ds_read_b64_tr_b16 v[214:215], v32 offset:33984
	ds_read_b64_tr_b16 v[216:217], v32 offset:36544
	v_exp_f32_e32 v144, v144
	v_exp_f32_e32 v145, v145
	v_cvt_pk_bf16_f32 v249, v140, v141
	v_add_f32_e32 v254, v254, v132
	v_add_f32_e32 v213, v213, v133
	s_waitcnt lgkmcnt(8)
	v_mfma_f32_32x32x16_bf16 v[34:49], v[244:247], v[218:221], v[34:49]
	v_cvt_pk_bf16_f32 v250, v142, v143
	v_add_f32_e32 v252, v252, v134
	v_cvt_pk_bf16_f32 v251, v144, v145
	v_add_f32_e32 v253, v253, v135
	v_add_f32_e32 v254, v254, v136
	v_add_f32_e32 v213, v213, v137
	s_waitcnt lgkmcnt(6)
	v_mfma_f32_32x32x16_bf16 v[82:97], v[248:251], v[222:225], v[82:97]
	v_add_f32_e32 v252, v252, v138
	v_add_f32_e32 v253, v253, v139
	v_add_f32_e32 v254, v254, v140
	s_waitcnt lgkmcnt(4)
	v_mfma_f32_32x32x16_bf16 v[66:81], v[248:251], v[226:229], v[66:81]
	v_add_f32_e32 v213, v213, v141
	v_add_f32_e32 v252, v252, v142
	v_add_f32_e32 v253, v253, v143
	s_waitcnt lgkmcnt(2)
	v_mfma_f32_32x32x16_bf16 v[50:65], v[248:251], v[230:233], v[50:65]
	v_add_f32_e32 v254, v254, v144
	v_add_f32_e32 v213, v213, v145
	v_add_f32_e32 v252, v252, v253
	v_add_f32_e32 v254, v254, v213
	s_waitcnt lgkmcnt(0)
	v_mfma_f32_32x32x16_bf16 v[34:49], v[248:251], v[214:217], v[34:49]
	v_add_f32_e32 v252, v252, v254
	v_add_f32_e32 v182, v182, v252
	s_setprio 0

; #define LAS __attribute__((address_space(3)))
; #define ATT_BAR() asm volatile("s_waitcnt lgkmcnt(0)\n\ts_barrier" ::: "memory")
; #define ATT_BAR() asm volatile("s_waitcnt vmcnt(0) lgkmcnt(0)\n\ts_barrier" ::: "memory")
; template <int DQK>
; __device__ __forceinline__ void attn_pass4(LAS unsigned char* lds, const bf16* Qp, int qpitch, const bf16* Kp, int kpitch, const bf16* Vp, int vpitch, int q0, f32x16 (&o)[4], float (&rl)[16]) {
;     ...
;     int tid = threadIdx.x; asm volatile("" : "+v"(tid));
;     const int lane = tid & 63, r32 = lane & 31, hi = lane >> 5;
;     const int wid = __builtin_amdgcn_readfirstlane(tid >> 6);
;     const bool shifted = wid >= 4;
;     LAS float* wsf = (LAS float*)(lds + G::WS_OFF) + wid * 64;
;     bf16x8 qf[DQK / 16];
;     { const bf16* qrow = Qp + (size_t)(q0 + wid * 32 + r32) * qpitch + 8 * hi;
; #pragma unroll
;       for (int d0 = 0; d0 < DQK / 16; ++d0) qf[d0] = *(const bf16x8*)(qrow + 16 * d0); }
;     const int NT = (q0 + 256) / 64;
;     const int qw0 = q0 + wid * 32;
;     const unsigned lds0 = (unsigned)(size_t)lds;
;     constexpr int KS = G::KP / 16, KD = DQK / 8, KJ = (KS + 7) / 8, VS = VP / 16, VD = 16, VJ = (VS + 7) / 8;
;     unsigned koff[KJ], voff[VJ];
; #pragma unroll
;     for (int j = 0; j < KJ; ++j) { const int sidx = (j * 8 + wid) * 64 + lane, row = (sidx / KS) & 63, c = sidx % KS; koff[j] = (unsigned)(row * kpitch + (c < KD ? c : KD - 1) * 8) * 2u; }
; #pragma unroll
;     for (int j = 0; j < VJ; ++j) { const int sidx = (j * 8 + wid) * 64 + lane, row = (sidx / VS) & 63, c = sidx % VS; voff[j] = (unsigned)(row * vpitch + (c < VD ? c : VD - 1) * 8) * 2u; }
;     ...
; #pragma unroll
;     for (int db = 0; db < 4; ++db)
; #pragma unroll
;         for (int r = 0; r < 16; ++r) o[db][r] = 0.f;
;     float mhat = 0.f, l = 0.f;
;     f32x16 negm;
; #pragma unroll
;     for (int r = 0; r < 16; ++r) negm[r] = 0.f;
;     ...
;     ATT_DMA(0, 0, 0); ATT_BAR();
;     int vcur = 0;
;     ...
;     if (!shifted) {
.LBB0_819:
	s_andn2_b32 s3, s3, 63
	s_lshl_b32 s3, s3, 2
	s_add_i32 s81, s3, 0
	s_waitcnt vmcnt(0) lgkmcnt(0)
	s_barrier
	v_and_b32_e32 v167, 63, v32
	s_add_i32 s81, s81, 0x13800
	v_mul_u32_u24_e32 v35, 0x90, v34
	v_lshlrev_b32_e32 v36, 1, v32
	v_lshlrev_b32_e32 v37, 3, v32
	s_cmp_lt_i32 s80, 8
	s_mov_b64 s[70:71], -1
	v_cmp_gt_u32_e64 s[8:9], 32, v167
	v_add3_u32 v188, 0, v35, v168
	v_lshlrev_b32_e32 v190, 2, v180
	v_lshl_add_u32 v169, v34, 2, s81
	v_lshrrev_b32_e32 v192, 2, v32
	v_and_b32_e32 v184, 32, v36
	v_and_b32_e32 v186, 24, v37
	s_cbranch_scc0 .LBB0_842
	v_and_or_b32 v32, v192, 3, v190
	v_mad_u32_u24 v32, v32, s82, 0
	v_mov_b32_e32 v46, v33
	v_mov_b32_e32 v47, v33
	v_add3_u32 v194, v32, v184, v186
	v_mov_b32_e32 v32, v33
	v_mov_b32_e32 v34, v33
	v_mov_b32_e32 v35, v33
	v_mov_b32_e32 v36, v33
	v_mov_b32_e32 v37, v33
	v_mov_b32_e32 v38, v33
	v_mov_b32_e32 v39, v33
	v_mov_b32_e32 v40, v33
	v_mov_b32_e32 v41, v33
	v_mov_b32_e32 v42, v33
	v_mov_b32_e32 v43, v33
	v_mov_b32_e32 v44, v33
	v_mov_b32_e32 v45, v33
	v_mov_b64_e32 v[96:97], v[46:47]
	v_mov_b64_e32 v[80:81], v[46:47]
	v_mov_b64_e32 v[64:65], v[46:47]
	s_lshl_b32 s3, s80, 10
	v_mov_b32_e32 v196, 0
	v_mov_b64_e32 v[94:95], v[44:45]
	v_mov_b64_e32 v[92:93], v[42:43]
	v_mov_b64_e32 v[90:91], v[40:41]
	v_mov_b64_e32 v[88:89], v[38:39]
	v_mov_b64_e32 v[86:87], v[36:37]
	v_mov_b64_e32 v[84:85], v[34:35]
	v_mov_b64_e32 v[82:83], v[32:33]
	v_mov_b64_e32 v[78:79], v[44:45]
	v_mov_b64_e32 v[76:77], v[42:43]
	v_mov_b64_e32 v[74:75], v[40:41]
	v_mov_b64_e32 v[72:73], v[38:39]
	v_mov_b64_e32 v[70:71], v[36:37]
	v_mov_b64_e32 v[68:69], v[34:35]
	v_mov_b64_e32 v[66:67], v[32:33]
	v_mov_b64_e32 v[62:63], v[44:45]
	v_mov_b64_e32 v[60:61], v[42:43]
	v_mov_b64_e32 v[58:59], v[40:41]
	v_mov_b64_e32 v[56:57], v[38:39]
	v_mov_b64_e32 v[54:55], v[36:37]
	v_mov_b64_e32 v[52:53], v[34:35]
	v_mov_b64_e32 v[50:51], v[32:33]
	v_mov_b64_e32 v[48:49], v[46:47]
	s_add_i32 s5, s3, 0x4800
	s_or_b32 s26, s76, 31
	v_mov_b32_e32 v171, v33
	v_mov_b32_e32 v177, v33
	s_lshl_b32 s27, s2, 10
	v_mov_b32_e32 v173, v33
	v_mov_b32_e32 v175, v33
	v_mov_b32_e32 v179, v33
	s_mov_b32 s35, 0
	s_mov_b32 s18, 63
	s_mov_b64 s[70:71], s[62:63]
	v_mov_b64_e32 v[46:47], v[44:45]
	v_mov_b64_e32 v[44:45], v[42:43]
	v_mov_b64_e32 v[42:43], v[40:41]
	v_mov_b64_e32 v[40:41], v[38:39]
	v_mov_b64_e32 v[38:39], v[36:37]
	v_mov_b64_e32 v[36:37], v[34:35]
	v_mov_b64_e32 v[34:35], v[32:33]
	v_mov_b32_e32 v182, 0
	s_mov_b32 s72, 0
	v_mov_b32_e32 v98, 0
	v_mov_b32_e32 v99, v196
	v_mov_b32_e32 v100, v196
	v_mov_b32_e32 v101, v196
	v_mov_b32_e32 v102, v196
	v_mov_b32_e32 v103, v196
	v_mov_b32_e32 v104, v196
	v_mov_b32_e32 v105, v196
	v_mov_b32_e32 v106, v196
	v_mov_b32_e32 v107, v196
	v_mov_b32_e32 v108, v196
	v_mov_b32_e32 v109, v196
	v_mov_b32_e32 v110, v196
	v_mov_b32_e32 v111, v196
	v_mov_b32_e32 v112, v196
	v_mov_b32_e32 v113, v196

.LBB0_824:
	s_add_u32 s74, s70, 0x3ffff80
	s_mul_i32 s73, s24, 0x5000
	s_addc_u32 s75, s71, 0
	s_add_i32 s73, s5, s73
	v_lshl_add_u64 v[114:115], s[74:75], 0, v[172:173]
	s_add_i32 s73, s73, 0
	s_mov_b32 vcc_lo, m0
	s_mov_b32 m0, s73
	s_nop 0
	global_load_lds_dwordx4 v[114:115], off
	s_mov_b32 m0, vcc_lo
	s_add_i32 vcc_lo, s73, 0x2000
	v_lshl_add_u64 v[114:115], s[74:75], 0, v[174:175]
	s_mov_b32 vcc_hi, m0
	s_mov_b32 m0, vcc_lo
	s_nop 0
	global_load_lds_dwordx4 v[114:115], off
	s_mov_b32 m0, vcc_hi
	v_readfirstlane_b32 s32, v242
	s_cmpk_gt_u32 s32, 0xff
	s_cbranch_scc1 .Lskip_v2_1
	v_lshl_add_u64 v[114:115], s[74:75], 0, v[178:179]
	s_addk_i32 s73, 0x4000
	s_mov_b32 s74, m0
	s_mov_b32 m0, s73
	s_nop 0
	global_load_lds_dwordx4 v[114:115], off
	s_mov_b32 m0, s74
.Lskip_v2_1:
.LBB0_825:
	s_sub_i32 s73, s18, 63
	s_cmp_gt_i32 s73, s26
	s_cbranch_scc1 .LBB0_838
	s_bitcmp1_b32 s72, 0
	s_cselect_b32 s72, 0x2400, 0
	v_add_u32_e32 v32, s72, v188
	s_setprio 1
	ds_read_b128 v[214:217], v32
	ds_read_b128 v[218:221], v32 offset:4608
	ds_read_b128 v[222:225], v32 offset:32
	ds_read_b128 v[226:229], v32 offset:4640
	ds_read_b128 v[230:233], v32 offset:64
	ds_read_b128 v[234:237], v32 offset:4672
	ds_read_b128 v[238:241], v32 offset:96
	ds_read_b128 v[244:247], v32 offset:4704
	s_waitcnt lgkmcnt(7)
	v_mfma_f32_32x32x16_bf16 v[114:129], v[214:217], v[146:149], v[98:113]
	s_waitcnt lgkmcnt(6)
	v_mfma_f32_32x32x16_bf16 v[130:145], v[218:221], v[146:149], v[98:113]
	s_waitcnt lgkmcnt(5)
	v_mfma_f32_32x32x16_bf16 v[114:129], v[222:225], v[150:153], v[114:129]
	s_waitcnt lgkmcnt(4)
	v_mfma_f32_32x32x16_bf16 v[130:145], v[226:229], v[150:153], v[130:145]
	s_waitcnt lgkmcnt(3)
	v_mfma_f32_32x32x16_bf16 v[114:129], v[230:233], v[154:157], v[114:129]
	s_waitcnt lgkmcnt(2)
	v_mfma_f32_32x32x16_bf16 v[130:145], v[234:237], v[154:157], v[130:145]
	s_waitcnt lgkmcnt(1)
	v_mfma_f32_32x32x16_bf16 v[114:129], v[238:241], v[158:161], v[114:129]
	s_waitcnt lgkmcnt(0)
	v_mfma_f32_32x32x16_bf16 v[130:145], v[244:247], v[158:161], v[130:145]
	s_setprio 0
	s_cmp_le_i32 s18, s76
	s_cbranch_scc1 .LBB0_828
	v_add_u32_e32 v32, s18, v190
	v_subrev_u32_e32 v200, 31, v32
	v_subrev_u32_e32 v198, 63, v32
	v_cmp_le_i32_e32 vcc, v200, v166
	s_nop 4
	v_cndmask_b32_e32 v130, v208, v130, vcc
	v_cmp_lt_i32_e32 vcc, v198, v166
	s_nop 1
	v_cndmask_b32_e32 v115, v208, v115, vcc
	v_cmp_le_i32_e32 vcc, v198, v166
	v_subrev_u32_e32 v198, 30, v32
	s_nop 0
	v_cndmask_b32_e32 v114, v208, v114, vcc
	v_cmp_le_i32_e32 vcc, v198, v166
	v_subrev_u32_e32 v198, 61, v32
	s_nop 0
	v_cndmask_b32_e32 v131, v208, v131, vcc
	v_cmp_le_i32_e32 vcc, v198, v166
	v_subrev_u32_e32 v198, 29, v32
	s_nop 0
	v_cndmask_b32_e32 v116, v208, v116, vcc
	v_cmp_le_i32_e32 vcc, v198, v166
	v_subrev_u32_e32 v198, 60, v32
	s_nop 0
	v_cndmask_b32_e32 v132, v208, v132, vcc
	v_cmp_le_i32_e32 vcc, v198, v166
	v_subrev_u32_e32 v198, 28, v32
	s_nop 0
	v_cndmask_b32_e32 v117, v208, v117, vcc
	v_cmp_le_i32_e32 vcc, v198, v166
	v_subrev_u32_e32 v198, 55, v32
	s_nop 0
	v_cndmask_b32_e32 v133, v208, v133, vcc
	v_cmp_le_i32_e32 vcc, v198, v166
	v_subrev_u32_e32 v198, 23, v32
	s_nop 0
	v_cndmask_b32_e32 v118, v208, v118, vcc
	v_cmp_le_i32_e32 vcc, v198, v166
	v_subrev_u32_e32 v198, 54, v32
	s_nop 0
	v_cndmask_b32_e32 v134, v208, v134, vcc
	v_cmp_le_i32_e32 vcc, v198, v166
	v_subrev_u32_e32 v198, 22, v32
	s_nop 0
	v_cndmask_b32_e32 v119, v208, v119, vcc
	v_cmp_le_i32_e32 vcc, v198, v166
	v_subrev_u32_e32 v198, 53, v32
	s_nop 0
	v_cndmask_b32_e32 v135, v208, v135, vcc
	v_cmp_le_i32_e32 vcc, v198, v166
	v_subrev_u32_e32 v198, 21, v32
	s_nop 0
	v_cndmask_b32_e32 v120, v208, v120, vcc
	v_cmp_le_i32_e32 vcc, v198, v166
	v_subrev_u32_e32 v198, 52, v32
	s_nop 0
	v_cndmask_b32_e32 v136, v208, v136, vcc
	v_cmp_le_i32_e32 vcc, v198, v166
	v_subrev_u32_e32 v198, 20, v32
	s_nop 0
	v_cndmask_b32_e32 v121, v208, v121, vcc
	v_cmp_le_i32_e32 vcc, v198, v166
	v_subrev_u32_e32 v198, 47, v32
	s_nop 0
	v_cndmask_b32_e32 v137, v208, v137, vcc
	v_cmp_le_i32_e32 vcc, v198, v166
	v_add_u32_e32 v198, -15, v32
	s_nop 0
	v_cndmask_b32_e32 v122, v208, v122, vcc
	v_cmp_le_i32_e32 vcc, v198, v166
	v_subrev_u32_e32 v198, 46, v32
	s_nop 0
	v_cndmask_b32_e32 v138, v208, v138, vcc
	v_cmp_le_i32_e32 vcc, v198, v166
	v_add_u32_e32 v198, -14, v32
	s_nop 0
	v_cndmask_b32_e32 v123, v208, v123, vcc
	v_cmp_le_i32_e32 vcc, v198, v166
	v_subrev_u32_e32 v198, 45, v32
	s_nop 0
	v_cndmask_b32_e32 v139, v208, v139, vcc
	v_cmp_le_i32_e32 vcc, v198, v166
	v_add_u32_e32 v198, -13, v32
	s_nop 0
	v_cndmask_b32_e32 v124, v208, v124, vcc
	v_cmp_le_i32_e32 vcc, v198, v166
	v_subrev_u32_e32 v198, 44, v32
	s_nop 0
	v_cndmask_b32_e32 v140, v208, v140, vcc
	v_cmp_le_i32_e32 vcc, v198, v166
	v_add_u32_e32 v198, -12, v32
	s_nop 0
	v_cndmask_b32_e32 v125, v208, v125, vcc
	v_cmp_le_i32_e32 vcc, v198, v166
	v_subrev_u32_e32 v198, 39, v32
	s_nop 0
	v_cndmask_b32_e32 v141, v208, v141, vcc
	v_cmp_le_i32_e32 vcc, v198, v166
	v_add_u32_e32 v198, -7, v32
	s_nop 0
	v_cndmask_b32_e32 v126, v208, v126, vcc
	v_cmp_le_i32_e32 vcc, v198, v166
	v_subrev_u32_e32 v198, 38, v32
	s_nop 0
	v_cndmask_b32_e32 v142, v208, v142, vcc
	v_cmp_le_i32_e32 vcc, v198, v166
	v_add_u32_e32 v198, -6, v32
	s_nop 0
	v_cndmask_b32_e32 v127, v208, v127, vcc
	v_cmp_le_i32_e32 vcc, v198, v166
	v_subrev_u32_e32 v198, 37, v32
	s_nop 0
	v_cndmask_b32_e32 v143, v208, v143, vcc
	v_cmp_le_i32_e32 vcc, v198, v166
	v_add_u32_e32 v198, -5, v32
	s_nop 0
	v_cndmask_b32_e32 v128, v208, v128, vcc
	v_cmp_le_i32_e32 vcc, v198, v166
	v_subrev_u32_e32 v198, 36, v32
	v_add_u32_e32 v32, -4, v32
	v_cndmask_b32_e32 v144, v208, v144, vcc
	v_cmp_le_i32_e32 vcc, v198, v166
	s_nop 1
	v_cndmask_b32_e32 v129, v208, v129, vcc
	v_cmp_le_i32_e32 vcc, v32, v166
	s_nop 1
	v_cndmask_b32_e32 v145, v208, v145, vcc

.LBB0_837:
	s_mulk_i32 s35, 0x5000
	v_add_u32_e32 v32, s35, v194
	s_setprio 1
	ds_read_b64_tr_b16 v[214:215], v32 offset:18432
	ds_read_b64_tr_b16 v[216:217], v32 offset:20992
	ds_read_b64_tr_b16 v[218:219], v32 offset:18496
	ds_read_b64_tr_b16 v[220:221], v32 offset:21056
	ds_read_b64_tr_b16 v[222:223], v32 offset:18560
	ds_read_b64_tr_b16 v[224:225], v32 offset:21120
	ds_read_b64_tr_b16 v[226:227], v32 offset:18624
	ds_read_b64_tr_b16 v[228:229], v32 offset:21184
	ds_read_b64_tr_b16 v[230:231], v32 offset:23552
	ds_read_b64_tr_b16 v[232:233], v32 offset:26112
	v_exp_f32_e32 v114, v114
	v_exp_f32_e32 v115, v115
	v_exp_f32_e32 v116, v116
	v_exp_f32_e32 v117, v117
	v_exp_f32_e32 v118, v118
	v_cvt_pk_bf16_f32 v234, v114, v115
	v_exp_f32_e32 v119, v119
	v_cvt_pk_bf16_f32 v235, v116, v117
	v_exp_f32_e32 v120, v120
	v_exp_f32_e32 v121, v121
	v_cvt_pk_bf16_f32 v236, v118, v119
	s_nop 0
	v_cvt_pk_bf16_f32 v237, v120, v121
	s_nop 1
	s_waitcnt lgkmcnt(8)
	v_mfma_f32_32x32x16_bf16 v[82:97], v[234:237], v[214:217], v[82:97]
	ds_read_b64_tr_b16 v[214:215], v32 offset:23616
	ds_read_b64_tr_b16 v[216:217], v32 offset:26176
	v_exp_f32_e32 v122, v122
	v_exp_f32_e32 v123, v123
	v_exp_f32_e32 v124, v124
	s_waitcnt lgkmcnt(8)
	v_mfma_f32_32x32x16_bf16 v[66:81], v[234:237], v[218:221], v[66:81]
	ds_read_b64_tr_b16 v[218:219], v32 offset:23680
	ds_read_b64_tr_b16 v[220:221], v32 offset:26240
	v_exp_f32_e32 v125, v125
	v_exp_f32_e32 v126, v126
	v_exp_f32_e32 v127, v127
	v_cvt_pk_bf16_f32 v238, v122, v123
	v_add_f32_e32 v252, v114, v115
	s_waitcnt lgkmcnt(8)
	v_mfma_f32_32x32x16_bf16 v[50:65], v[234:237], v[222:225], v[50:65]
	ds_read_b64_tr_b16 v[222:223], v32 offset:23744
	ds_read_b64_tr_b16 v[224:225], v32 offset:26304
	v_exp_f32_e32 v128, v128
	v_exp_f32_e32 v129, v129
	v_cvt_pk_bf16_f32 v239, v124, v125
	v_add_f32_e32 v253, v116, v117
	s_waitcnt lgkmcnt(8)
	v_mfma_f32_32x32x16_bf16 v[34:49], v[234:237], v[226:229], v[34:49]
	ds_read_b64_tr_b16 v[226:227], v32 offset:28672
	ds_read_b64_tr_b16 v[228:229], v32 offset:31232
	v_cvt_pk_bf16_f32 v240, v126, v127
	v_cvt_pk_bf16_f32 v241, v128, v129
	v_add_f32_e32 v254, v118, v119
	v_add_f32_e32 v213, v120, v121
	s_waitcnt lgkmcnt(8)
	v_mfma_f32_32x32x16_bf16 v[82:97], v[238:241], v[230:233], v[82:97]
	ds_read_b64_tr_b16 v[230:231], v32 offset:28736
	ds_read_b64_tr_b16 v[232:233], v32 offset:31296
	v_exp_f32_e32 v130, v130
	v_exp_f32_e32 v131, v131
	v_exp_f32_e32 v132, v132
	v_add_f32_e32 v252, v252, v122
	s_waitcnt lgkmcnt(8)
	v_mfma_f32_32x32x16_bf16 v[66:81], v[238:241], v[214:217], v[66:81]
	ds_read_b64_tr_b16 v[214:215], v32 offset:28800
	ds_read_b64_tr_b16 v[216:217], v32 offset:31360
	v_exp_f32_e32 v133, v133
	v_exp_f32_e32 v134, v134
	v_exp_f32_e32 v135, v135
	v_cvt_pk_bf16_f32 v244, v130, v131
	v_add_f32_e32 v253, v253, v123
	s_waitcnt lgkmcnt(8)
	v_mfma_f32_32x32x16_bf16 v[50:65], v[238:241], v[218:221], v[50:65]
	ds_read_b64_tr_b16 v[218:219], v32 offset:28864
	ds_read_b64_tr_b16 v[220:221], v32 offset:31424
	v_exp_f32_e32 v136, v136
	v_exp_f32_e32 v137, v137
	v_cvt_pk_bf16_f32 v245, v132, v133
	v_add_f32_e32 v254, v254, v124
	v_add_f32_e32 v213, v213, v125
	s_waitcnt lgkmcnt(8)
	v_mfma_f32_32x32x16_bf16 v[34:49], v[238:241], v[222:225], v[34:49]
	ds_read_b64_tr_b16 v[222:223], v32 offset:33792
	ds_read_b64_tr_b16 v[224:225], v32 offset:36352
	v_cvt_pk_bf16_f32 v246, v134, v135
	v_add_f32_e32 v252, v252, v126
	v_cvt_pk_bf16_f32 v247, v136, v137
	v_add_f32_e32 v253, v253, v127
	v_add_f32_e32 v254, v254, v128
	v_add_f32_e32 v213, v213, v129
	s_waitcnt lgkmcnt(8)
	v_mfma_f32_32x32x16_bf16 v[82:97], v[244:247], v[226:229], v[82:97]
	ds_read_b64_tr_b16 v[226:227], v32 offset:33856
	ds_read_b64_tr_b16 v[228:229], v32 offset:36416
	v_exp_f32_e32 v138, v138
	v_exp_f32_e32 v139, v139
	v_exp_f32_e32 v140, v140
	v_add_f32_e32 v252, v252, v130
	s_waitcnt lgkmcnt(8)
	v_mfma_f32_32x32x16_bf16 v[66:81], v[244:247], v[230:233], v[66:81]
	ds_read_b64_tr_b16 v[230:231], v32 offset:33920
	ds_read_b64_tr_b16 v[232:233], v32 offset:36480
	v_exp_f32_e32 v141, v141
	v_exp_f32_e32 v142, v142
	v_exp_f32_e32 v143, v143
	v_cvt_pk_bf16_f32 v248, v138, v139
	v_add_f32_e32 v253, v253, v131
	s_waitcnt lgkmcnt(8)
	v_mfma_f32_32x32x16_bf16 v[50:65], v[244:247], v[214:217], v[50:65]
	ds_read_b64_tr_b16 v[214:215], v32 offset:33984
	ds_read_b64_tr_b16 v[216:217], v32 offset:36544
	v_exp_f32_e32 v144, v144
	v_exp_f32_e32 v145, v145
	v_cvt_pk_bf16_f32 v249, v140, v141
	v_add_f32_e32 v254, v254, v132
	v_add_f32_e32 v213, v213, v133
	s_waitcnt lgkmcnt(8)
	v_mfma_f32_32x32x16_bf16 v[34:49], v[244:247], v[218:221], v[34:49]
	v_cvt_pk_bf16_f32 v250, v142, v143
	v_add_f32_e32 v252, v252, v134
	v_cvt_pk_bf16_f32 v251, v144, v145
	v_add_f32_e32 v253, v253, v135
	v_add_f32_e32 v254, v254, v136
	v_add_f32_e32 v213, v213, v137
	s_waitcnt lgkmcnt(6)
	v_mfma_f32_32x32x16_bf16 v[82:97], v[248:251], v[222:225], v[82:97]
	v_add_f32_e32 v252, v252, v138
	v_add_f32_e32 v253, v253, v139
	v_add_f32_e32 v254, v254, v140
	s_waitcnt lgkmcnt(4)
	v_mfma_f32_32x32x16_bf16 v[66:81], v[248:251], v[226:229], v[66:81]
	v_add_f32_e32 v213, v213, v141
	v_add_f32_e32 v252, v252, v142
	v_add_f32_e32 v253, v253, v143
	s_waitcnt lgkmcnt(2)
	v_mfma_f32_32x32x16_bf16 v[50:65], v[248:251], v[230:233], v[50:65]
	v_add_f32_e32 v254, v254, v144
	v_add_f32_e32 v213, v213, v145
	v_add_f32_e32 v252, v252, v253
	v_add_f32_e32 v254, v254, v213
	s_waitcnt lgkmcnt(0)
	v_mfma_f32_32x32x16_bf16 v[34:49], v[248:251], v[214:217], v[34:49]
	v_add_f32_e32 v252, v252, v254
	v_add_f32_e32 v182, v182, v252
	s_setprio 0

; #define ATT_BAR() asm volatile("s_waitcnt lgkmcnt(0)\n\ts_barrier" ::: "memory")
; #define ATT_BAR() asm volatile("s_waitcnt vmcnt(0) lgkmcnt(0)\n\ts_barrier" ::: "memory")
; template <int DQK>
; __device__ __forceinline__ void attn_pass4(LAS unsigned char* lds, const bf16* Qp, int qpitch, const bf16* Kp, int kpitch, const bf16* Vp, int vpitch, int q0, f32x16 (&o)[4], float (&rl)[16]) {
;     ...
;     const int NT = (q0 + 256) / 64;
;     const int qw0 = q0 + wid * 32;
;     const unsigned lds0 = (unsigned)(size_t)lds;
;     constexpr int KS = G::KP / 16, KD = DQK / 8, KJ = (KS + 7) / 8, VS = VP / 16, VD = 16, VJ = (VS + 7) / 8;
;     unsigned koff[KJ], voff[VJ];
; #pragma unroll
;     for (int j = 0; j < KJ; ++j) { const int sidx = (j * 8 + wid) * 64 + lane, row = (sidx / KS) & 63, c = sidx % KS; koff[j] = (unsigned)(row * kpitch + (c < KD ? c : KD - 1) * 8) * 2u; }
; #pragma unroll
;     for (int j = 0; j < VJ; ++j) { const int sidx = (j * 8 + wid) * 64 + lane, row = (sidx / VS) & 63, c = sidx % VS; voff[j] = (unsigned)(row * vpitch + (c < VD ? c : VD - 1) * 8) * 2u; }
;     ...
; #pragma unroll
;     for (int db = 0; db < 4; ++db)
; #pragma unroll
;         for (int r = 0; r < 16; ++r) o[db][r] = 0.f;
;     float mhat = 0.f, l = 0.f;
;     f32x16 negm;
; #pragma unroll
;     for (int r = 0; r < 16; ++r) negm[r] = 0.f;
;     ...
;     ATT_DMA(0, 0, 0); ATT_BAR();
;     int vcur = 0;
;     ...
;     if (!shifted) {
;         for (int t = 0; t < NT; ++t) {
.LBB0_2149:
	s_andn2_b32 s2, s2, 63
	s_lshl_b32 s2, s2, 2
	s_add_i32 s10, s66, 0x100
	s_add_i32 s3, s2, 0
	s_waitcnt vmcnt(0) lgkmcnt(0)
	s_barrier
	v_and_b32_e32 v179, 63, v0
	s_add_i32 s3, s3, 0x1b800
	s_lshr_b32 s69, s10, 6
	v_mul_u32_u24_e32 v3, 0x190, v2
	v_lshlrev_b32_e32 v4, 1, v0
	v_lshlrev_b32_e32 v5, 3, v0
	s_cmp_lt_i32 s67, 8
	s_mov_b64 s[56:57], -1
	v_cmp_gt_u32_e64 s[10:11], 32, v179
	v_add3_u32 v200, 0, v3, v178
	v_lshlrev_b32_e32 v201, 2, v195
	v_lshl_add_u32 v196, v2, 2, s3
	v_lshrrev_b32_e32 v202, 2, v0
	v_and_b32_e32 v198, 32, v4
	v_and_b32_e32 v199, 24, v5
	s_cbranch_scc0 .LBB0_2172
	v_and_or_b32 v0, v202, 3, v201
	v_mad_u32_u24 v0, v0, s30, 0
	v_mov_b32_e32 v14, v1
	v_mov_b32_e32 v15, v1
	s_lshl_b32 s2, s67, 10
	v_add3_u32 v203, v0, v198, v199
	v_mov_b32_e32 v0, v1
	v_mov_b32_e32 v2, v1
	v_mov_b32_e32 v3, v1
	v_mov_b32_e32 v4, v1
	v_mov_b32_e32 v5, v1
	v_mov_b32_e32 v6, v1
	v_mov_b32_e32 v7, v1
	v_mov_b32_e32 v8, v1
	v_mov_b32_e32 v9, v1
	v_mov_b32_e32 v10, v1
	v_mov_b32_e32 v11, v1
	v_mov_b32_e32 v12, v1
	v_mov_b32_e32 v13, v1
	v_mov_b32_e32 v204, 0
	v_mov_b64_e32 v[30:31], v[14:15]
	v_mov_b64_e32 v[46:47], v[14:15]
	v_mov_b64_e32 v[62:63], v[14:15]
	v_mov_b64_e32 v[78:79], v[14:15]
	s_add_i32 s24, s2, 0xc800
	s_or_b32 s25, s68, 31
	v_mov_b32_e32 v181, v1
	v_mov_b32_e32 v183, v1
	s_lshl_b32 s72, s70, 10
	v_mov_b32_e32 v185, v1
	s_lshl_b32 s73, s71, 10
	v_mov_b32_e32 v191, v1
	s_lshl_b32 s74, s58, 10
	v_mov_b32_e32 v187, v1
	v_mov_b32_e32 v189, v1
	v_mov_b32_e32 v193, v1
	s_mov_b32 s78, 0
	s_mov_b32 s75, 63
	s_mov_b64 s[56:57], s[42:43]
	s_mov_b64 s[58:59], s[40:41]
	v_mov_b64_e32 v[28:29], v[12:13]
	v_mov_b64_e32 v[26:27], v[10:11]
	v_mov_b64_e32 v[24:25], v[8:9]
	v_mov_b64_e32 v[22:23], v[6:7]
	v_mov_b64_e32 v[20:21], v[4:5]
	v_mov_b64_e32 v[18:19], v[2:3]
	v_mov_b64_e32 v[16:17], v[0:1]
	v_mov_b64_e32 v[44:45], v[12:13]
	v_mov_b64_e32 v[42:43], v[10:11]
	v_mov_b64_e32 v[40:41], v[8:9]
	v_mov_b64_e32 v[38:39], v[6:7]
	v_mov_b64_e32 v[36:37], v[4:5]
	v_mov_b64_e32 v[34:35], v[2:3]
	v_mov_b64_e32 v[32:33], v[0:1]
	v_mov_b64_e32 v[60:61], v[12:13]
	v_mov_b64_e32 v[58:59], v[10:11]
	v_mov_b64_e32 v[56:57], v[8:9]
	v_mov_b64_e32 v[54:55], v[6:7]
	v_mov_b64_e32 v[52:53], v[4:5]
	v_mov_b64_e32 v[50:51], v[2:3]
	v_mov_b64_e32 v[48:49], v[0:1]
	v_mov_b64_e32 v[76:77], v[12:13]
	v_mov_b64_e32 v[74:75], v[10:11]
	v_mov_b64_e32 v[72:73], v[8:9]
	v_mov_b64_e32 v[70:71], v[6:7]
	v_mov_b64_e32 v[68:69], v[4:5]
	v_mov_b64_e32 v[66:67], v[2:3]
	v_mov_b64_e32 v[64:65], v[0:1]
	v_mov_b32_e32 v2, 0
	s_mov_b32 s60, 0
	v_mov_b32_e32 v80, 0
	v_mov_b32_e32 v81, v204
	v_mov_b32_e32 v82, v204
	v_mov_b32_e32 v83, v204
	v_mov_b32_e32 v84, v204
	v_mov_b32_e32 v85, v204
	v_mov_b32_e32 v86, v204
	v_mov_b32_e32 v87, v204
	v_mov_b32_e32 v88, v204
	v_mov_b32_e32 v89, v204
	v_mov_b32_e32 v90, v204
	v_mov_b32_e32 v91, v204
	v_mov_b32_e32 v92, v204
	v_mov_b32_e32 v93, v204
	v_mov_b32_e32 v94, v204
	v_mov_b32_e32 v95, v204

; template <int DQK>
; __device__ __forceinline__ void attn_pass4(LAS unsigned char* lds, const bf16* Qp, int qpitch, const bf16* Kp, int kpitch, const bf16* Vp, int vpitch, int q0, f32x16 (&o)[4], float (&rl)[16]) {
;     ...
;             if (t + 1 < NT) ATT_DMA(t + 1, (t + 1) & 1, vnext);
.LBB0_2154:
	s_mul_i32 s61, s76, 0x5000
	s_add_i32 s61, s24, s61
	v_lshl_add_u64 v[4:5], s[58:59], 0, v[186:187]
	s_add_i32 s61, s61, 0
	s_mov_b32 s62, m0
	s_mov_b32 m0, s61
	s_nop 0
	global_load_lds_dwordx4 v[4:5], off
	s_mov_b32 m0, s62
	v_lshl_add_u64 v[4:5], s[58:59], 0, v[188:189]
	s_add_i32 s62, s61, 0x2000
	s_mov_b32 s63, m0
	s_mov_b32 m0, s62
	s_nop 0
	global_load_lds_dwordx4 v[4:5], off
	s_mov_b32 m0, s63
	v_readfirstlane_b32 s32, v242
	s_cmpk_gt_u32 s32, 0xff
	s_cbranch_scc1 .Lskip_v2_2
	v_lshl_add_u64 v[4:5], s[58:59], 0, v[192:193]
	s_addk_i32 s61, 0x4000
	s_mov_b32 s62, m0
	s_mov_b32 m0, s61
	s_nop 0
	global_load_lds_dwordx4 v[4:5], off
	s_mov_b32 m0, s62
.Lskip_v2_2:
.LBB0_2155:
	s_sub_i32 s61, s75, 63
	s_cmp_gt_i32 s61, s25
	s_cbranch_scc1 .LBB0_2168
	s_bitcmp1_b32 s60, 0
	s_cselect_b32 s60, 0x6400, 0
	v_add_u32_e32 v0, s60, v200
	s_setprio 1
	ds_read_b128 v[214:217], v0
	ds_read_b128 v[218:221], v0 offset:32
	ds_read_b128 v[222:225], v0 offset:12800
	ds_read_b128 v[226:229], v0 offset:12832
	ds_read_b128 v[230:233], v0 offset:64
	ds_read_b128 v[234:237], v0 offset:12864
	ds_read_b128 v[238:241], v0 offset:96
	ds_read_b128 v[244:247], v0 offset:12896
	ds_read_b128 v[248:251], v0 offset:128
	s_waitcnt lgkmcnt(8)
	v_mfma_f32_32x32x16_bf16 v[96:111], v[214:217], v[128:131], v[80:95]
	ds_read_b128 v[214:217], v0 offset:12928
	s_waitcnt lgkmcnt(8)
	v_mfma_f32_32x32x16_bf16 v[96:111], v[218:221], v[132:135], v[96:111]
	ds_read_b128 v[218:221], v0 offset:160
	s_waitcnt lgkmcnt(8)
	v_mfma_f32_32x32x16_bf16 v[112:127], v[222:225], v[128:131], v[80:95]
	ds_read_b128 v[222:225], v0 offset:12960
	s_waitcnt lgkmcnt(8)
	v_mfma_f32_32x32x16_bf16 v[112:127], v[226:229], v[132:135], v[112:127]
	ds_read_b128 v[226:229], v0 offset:192
	s_waitcnt lgkmcnt(8)
	v_mfma_f32_32x32x16_bf16 v[96:111], v[230:233], v[136:139], v[96:111]
	ds_read_b128 v[230:233], v0 offset:12992
	s_waitcnt lgkmcnt(8)
	v_mfma_f32_32x32x16_bf16 v[112:127], v[234:237], v[136:139], v[112:127]
	ds_read_b128 v[234:237], v0 offset:224
	s_waitcnt lgkmcnt(8)
	v_mfma_f32_32x32x16_bf16 v[96:111], v[238:241], v[140:143], v[96:111]
	ds_read_b128 v[238:241], v0 offset:13024
	s_waitcnt lgkmcnt(8)
	v_mfma_f32_32x32x16_bf16 v[112:127], v[244:247], v[140:143], v[112:127]
	ds_read_b128 v[244:247], v0 offset:256
	s_waitcnt lgkmcnt(8)
	v_mfma_f32_32x32x16_bf16 v[96:111], v[248:251], v[144:147], v[96:111]
	ds_read_b128 v[248:251], v0 offset:13056
	s_waitcnt lgkmcnt(8)
	v_mfma_f32_32x32x16_bf16 v[112:127], v[214:217], v[144:147], v[112:127]
	ds_read_b128 v[214:217], v0 offset:288
	s_waitcnt lgkmcnt(8)
	v_mfma_f32_32x32x16_bf16 v[96:111], v[218:221], v[148:151], v[96:111]
	ds_read_b128 v[218:221], v0 offset:13088
	s_waitcnt lgkmcnt(8)
	v_mfma_f32_32x32x16_bf16 v[112:127], v[222:225], v[148:151], v[112:127]
	ds_read_b128 v[222:225], v0 offset:320
	s_waitcnt lgkmcnt(8)
	v_mfma_f32_32x32x16_bf16 v[96:111], v[226:229], v[152:155], v[96:111]
	ds_read_b128 v[226:229], v0 offset:13120
	s_waitcnt lgkmcnt(8)
	v_mfma_f32_32x32x16_bf16 v[112:127], v[230:233], v[152:155], v[112:127]
	ds_read_b128 v[230:233], v0 offset:352
	s_waitcnt lgkmcnt(8)
	v_mfma_f32_32x32x16_bf16 v[96:111], v[234:237], v[156:159], v[96:111]
	ds_read_b128 v[234:237], v0 offset:13152
	s_waitcnt lgkmcnt(8)
	v_mfma_f32_32x32x16_bf16 v[112:127], v[238:241], v[156:159], v[112:127]
	s_waitcnt lgkmcnt(7)
	v_mfma_f32_32x32x16_bf16 v[96:111], v[244:247], v[160:163], v[96:111]
	s_waitcnt lgkmcnt(6)
	v_mfma_f32_32x32x16_bf16 v[112:127], v[248:251], v[160:163], v[112:127]
	s_waitcnt lgkmcnt(5)
	v_mfma_f32_32x32x16_bf16 v[96:111], v[214:217], v[164:167], v[96:111]
	s_waitcnt lgkmcnt(4)
	v_mfma_f32_32x32x16_bf16 v[112:127], v[218:221], v[164:167], v[112:127]
	s_waitcnt lgkmcnt(3)
	v_mfma_f32_32x32x16_bf16 v[96:111], v[222:225], v[168:171], v[96:111]
	s_waitcnt lgkmcnt(2)
	v_mfma_f32_32x32x16_bf16 v[112:127], v[226:229], v[168:171], v[112:127]
	s_waitcnt lgkmcnt(1)
	v_mfma_f32_32x32x16_bf16 v[96:111], v[230:233], v[172:175], v[96:111]
	s_waitcnt lgkmcnt(0)
	v_mfma_f32_32x32x16_bf16 v[112:127], v[234:237], v[172:175], v[112:127]
	s_setprio 0
	s_cmp_le_i32 s75, s68
	s_cbranch_scc1 .LBB0_2158
	v_add_u32_e32 v0, s75, v201
	v_subrev_u32_e32 v4, 31, v0
	v_subrev_u32_e32 v3, 63, v0
	v_cmp_le_i32_e32 vcc, v4, v197
	s_nop 4
	v_cndmask_b32_e32 v112, v194, v112, vcc
	v_cmp_lt_i32_e32 vcc, v3, v197
	s_nop 1
	v_cndmask_b32_e32 v97, v194, v97, vcc
	v_cmp_le_i32_e32 vcc, v3, v197
	v_subrev_u32_e32 v3, 30, v0
	s_nop 0
	v_cndmask_b32_e32 v96, v194, v96, vcc
	v_cmp_le_i32_e32 vcc, v3, v197
	v_subrev_u32_e32 v3, 61, v0
	s_nop 0
	v_cndmask_b32_e32 v113, v194, v113, vcc
	v_cmp_le_i32_e32 vcc, v3, v197
	v_subrev_u32_e32 v3, 29, v0
	s_nop 0
	v_cndmask_b32_e32 v98, v194, v98, vcc
	v_cmp_le_i32_e32 vcc, v3, v197
	v_subrev_u32_e32 v3, 60, v0
	s_nop 0
	v_cndmask_b32_e32 v114, v194, v114, vcc
	v_cmp_le_i32_e32 vcc, v3, v197
	v_subrev_u32_e32 v3, 28, v0
	s_nop 0
	v_cndmask_b32_e32 v99, v194, v99, vcc
	v_cmp_le_i32_e32 vcc, v3, v197
	v_subrev_u32_e32 v3, 55, v0
	s_nop 0
	v_cndmask_b32_e32 v115, v194, v115, vcc
	v_cmp_le_i32_e32 vcc, v3, v197
	v_subrev_u32_e32 v3, 23, v0
	s_nop 0
	v_cndmask_b32_e32 v100, v194, v100, vcc
	v_cmp_le_i32_e32 vcc, v3, v197
	v_subrev_u32_e32 v3, 54, v0
	s_nop 0
	v_cndmask_b32_e32 v116, v194, v116, vcc
	v_cmp_le_i32_e32 vcc, v3, v197
	v_subrev_u32_e32 v3, 22, v0
	s_nop 0
	v_cndmask_b32_e32 v101, v194, v101, vcc
	v_cmp_le_i32_e32 vcc, v3, v197
	v_subrev_u32_e32 v3, 53, v0
	s_nop 0
	v_cndmask_b32_e32 v117, v194, v117, vcc
	v_cmp_le_i32_e32 vcc, v3, v197
	v_subrev_u32_e32 v3, 21, v0
	s_nop 0
	v_cndmask_b32_e32 v102, v194, v102, vcc
	v_cmp_le_i32_e32 vcc, v3, v197
	v_subrev_u32_e32 v3, 52, v0
	s_nop 0
	v_cndmask_b32_e32 v118, v194, v118, vcc
	v_cmp_le_i32_e32 vcc, v3, v197
	v_subrev_u32_e32 v3, 20, v0
	s_nop 0
	v_cndmask_b32_e32 v103, v194, v103, vcc
	v_cmp_le_i32_e32 vcc, v3, v197
	v_subrev_u32_e32 v3, 47, v0
	s_nop 0
	v_cndmask_b32_e32 v119, v194, v119, vcc
	v_cmp_le_i32_e32 vcc, v3, v197
	v_add_u32_e32 v3, -15, v0
	s_nop 0
	v_cndmask_b32_e32 v104, v194, v104, vcc
	v_cmp_le_i32_e32 vcc, v3, v197
	v_subrev_u32_e32 v3, 46, v0
	s_nop 0
	v_cndmask_b32_e32 v120, v194, v120, vcc
	v_cmp_le_i32_e32 vcc, v3, v197
	v_add_u32_e32 v3, -14, v0
	s_nop 0
	v_cndmask_b32_e32 v105, v194, v105, vcc
	v_cmp_le_i32_e32 vcc, v3, v197
	v_subrev_u32_e32 v3, 45, v0
	s_nop 0
	v_cndmask_b32_e32 v121, v194, v121, vcc
	v_cmp_le_i32_e32 vcc, v3, v197
	v_add_u32_e32 v3, -13, v0
	s_nop 0
	v_cndmask_b32_e32 v106, v194, v106, vcc
	v_cmp_le_i32_e32 vcc, v3, v197
	v_subrev_u32_e32 v3, 44, v0
	s_nop 0
	v_cndmask_b32_e32 v122, v194, v122, vcc
	v_cmp_le_i32_e32 vcc, v3, v197
	v_add_u32_e32 v3, -12, v0
	s_nop 0
	v_cndmask_b32_e32 v107, v194, v107, vcc
	v_cmp_le_i32_e32 vcc, v3, v197
	v_subrev_u32_e32 v3, 39, v0
	s_nop 0
	v_cndmask_b32_e32 v123, v194, v123, vcc
	v_cmp_le_i32_e32 vcc, v3, v197
	v_add_u32_e32 v3, -7, v0
	s_nop 0
	v_cndmask_b32_e32 v108, v194, v108, vcc
	v_cmp_le_i32_e32 vcc, v3, v197
	v_subrev_u32_e32 v3, 38, v0
	s_nop 0
	v_cndmask_b32_e32 v124, v194, v124, vcc
	v_cmp_le_i32_e32 vcc, v3, v197
	v_add_u32_e32 v3, -6, v0
	s_nop 0
	v_cndmask_b32_e32 v109, v194, v109, vcc
	v_cmp_le_i32_e32 vcc, v3, v197
	v_subrev_u32_e32 v3, 37, v0
	s_nop 0
	v_cndmask_b32_e32 v125, v194, v125, vcc
	v_cmp_le_i32_e32 vcc, v3, v197
	v_add_u32_e32 v3, -5, v0
	s_nop 0
	v_cndmask_b32_e32 v110, v194, v110, vcc
	v_cmp_le_i32_e32 vcc, v3, v197
	v_subrev_u32_e32 v3, 36, v0
	v_add_u32_e32 v0, -4, v0
	v_cndmask_b32_e32 v126, v194, v126, vcc
	v_cmp_le_i32_e32 vcc, v3, v197
	s_nop 1
	v_cndmask_b32_e32 v111, v194, v111, vcc
	v_cmp_le_i32_e32 vcc, v0, v197
	s_nop 1
	v_cndmask_b32_e32 v127, v194, v127, vcc

.LBB0_2167:
	s_mulk_i32 s78, 0x5000
	v_add_u32_e32 v0, s78, v203
	v_add_u32_e32 v3, 0xc800, v0
	s_setprio 1
	ds_read_b64_tr_b16 v[214:215], v0 offset:51200
	ds_read_b64_tr_b16 v[216:217], v0 offset:53760
	ds_read_b64_tr_b16 v[218:219], v0 offset:51264
	ds_read_b64_tr_b16 v[220:221], v0 offset:53824
	ds_read_b64_tr_b16 v[222:223], v0 offset:51328
	ds_read_b64_tr_b16 v[224:225], v0 offset:53888
	ds_read_b64_tr_b16 v[226:227], v0 offset:51392
	ds_read_b64_tr_b16 v[228:229], v0 offset:53952
	ds_read_b64_tr_b16 v[230:231], v0 offset:56320
	ds_read_b64_tr_b16 v[232:233], v0 offset:58880
	v_exp_f32_e32 v96, v96
	v_exp_f32_e32 v97, v97
	v_exp_f32_e32 v98, v98
	v_exp_f32_e32 v99, v99
	v_exp_f32_e32 v100, v100
	v_cvt_pk_bf16_f32 v234, v96, v97
	v_exp_f32_e32 v101, v101
	v_cvt_pk_bf16_f32 v235, v98, v99
	v_exp_f32_e32 v102, v102
	v_exp_f32_e32 v103, v103
	v_cvt_pk_bf16_f32 v236, v100, v101
	s_nop 0
	v_cvt_pk_bf16_f32 v237, v102, v103
	s_nop 1
	s_waitcnt lgkmcnt(8)
	v_mfma_f32_32x32x16_bf16 v[64:79], v[234:237], v[214:217], v[64:79]
	ds_read_b64_tr_b16 v[214:215], v0 offset:56384
	ds_read_b64_tr_b16 v[216:217], v0 offset:58944
	v_exp_f32_e32 v104, v104
	v_exp_f32_e32 v105, v105
	v_exp_f32_e32 v106, v106
	s_waitcnt lgkmcnt(8)
	v_mfma_f32_32x32x16_bf16 v[48:63], v[234:237], v[218:221], v[48:63]
	ds_read_b64_tr_b16 v[218:219], v0 offset:56448
	ds_read_b64_tr_b16 v[220:221], v0 offset:59008
	v_exp_f32_e32 v107, v107
	v_exp_f32_e32 v108, v108
	v_exp_f32_e32 v109, v109
	v_cvt_pk_bf16_f32 v238, v104, v105
	v_add_f32_e32 v252, v96, v97
	s_waitcnt lgkmcnt(8)
	v_mfma_f32_32x32x16_bf16 v[32:47], v[234:237], v[222:225], v[32:47]
	ds_read_b64_tr_b16 v[222:223], v0 offset:56512
	ds_read_b64_tr_b16 v[224:225], v0 offset:59072
	v_exp_f32_e32 v110, v110
	v_exp_f32_e32 v111, v111
	v_cvt_pk_bf16_f32 v239, v106, v107
	v_add_f32_e32 v253, v98, v99
	s_waitcnt lgkmcnt(8)
	v_mfma_f32_32x32x16_bf16 v[16:31], v[234:237], v[226:229], v[16:31]
	ds_read_b64_tr_b16 v[226:227], v0 offset:61440
	ds_read_b64_tr_b16 v[228:229], v0 offset:64000
	v_cvt_pk_bf16_f32 v240, v108, v109
	v_cvt_pk_bf16_f32 v241, v110, v111
	v_add_f32_e32 v254, v100, v101
	v_add_f32_e32 v213, v102, v103
	s_waitcnt lgkmcnt(8)
	v_mfma_f32_32x32x16_bf16 v[64:79], v[238:241], v[230:233], v[64:79]
	ds_read_b64_tr_b16 v[230:231], v0 offset:61504
	ds_read_b64_tr_b16 v[232:233], v0 offset:64064
	v_exp_f32_e32 v112, v112
	v_exp_f32_e32 v113, v113
	v_exp_f32_e32 v114, v114
	v_add_f32_e32 v252, v252, v104
	s_waitcnt lgkmcnt(8)
	v_mfma_f32_32x32x16_bf16 v[48:63], v[238:241], v[214:217], v[48:63]
	ds_read_b64_tr_b16 v[214:215], v0 offset:61568
	ds_read_b64_tr_b16 v[216:217], v0 offset:64128
	v_exp_f32_e32 v115, v115
	v_exp_f32_e32 v116, v116
	v_exp_f32_e32 v117, v117
	v_cvt_pk_bf16_f32 v244, v112, v113
	v_add_f32_e32 v253, v253, v105
	s_waitcnt lgkmcnt(8)
	v_mfma_f32_32x32x16_bf16 v[32:47], v[238:241], v[218:221], v[32:47]
	ds_read_b64_tr_b16 v[218:219], v0 offset:61632
	ds_read_b64_tr_b16 v[220:221], v0 offset:64192
	v_exp_f32_e32 v118, v118
	v_exp_f32_e32 v119, v119
	v_cvt_pk_bf16_f32 v245, v114, v115
	v_add_f32_e32 v254, v254, v106
	v_add_f32_e32 v213, v213, v107
	s_waitcnt lgkmcnt(8)
	v_mfma_f32_32x32x16_bf16 v[16:31], v[238:241], v[222:225], v[16:31]
	ds_read_b64_tr_b16 v[222:223], v3 offset:15360
	ds_read_b64_tr_b16 v[224:225], v3 offset:17920
	v_cvt_pk_bf16_f32 v246, v116, v117
	v_add_f32_e32 v252, v252, v108
	v_cvt_pk_bf16_f32 v247, v118, v119
	v_add_f32_e32 v253, v253, v109
	v_add_f32_e32 v254, v254, v110
	v_add_f32_e32 v213, v213, v111
	s_waitcnt lgkmcnt(8)
	v_mfma_f32_32x32x16_bf16 v[64:79], v[244:247], v[226:229], v[64:79]
	ds_read_b64_tr_b16 v[226:227], v3 offset:15424
	ds_read_b64_tr_b16 v[228:229], v3 offset:17984
	v_exp_f32_e32 v120, v120
	v_exp_f32_e32 v121, v121
	v_exp_f32_e32 v122, v122
	v_add_f32_e32 v252, v252, v112
	s_waitcnt lgkmcnt(8)
	v_mfma_f32_32x32x16_bf16 v[48:63], v[244:247], v[230:233], v[48:63]
	ds_read_b64_tr_b16 v[230:231], v3 offset:15488
	ds_read_b64_tr_b16 v[232:233], v3 offset:18048
	v_exp_f32_e32 v123, v123
	v_exp_f32_e32 v124, v124
	v_exp_f32_e32 v125, v125
	v_cvt_pk_bf16_f32 v248, v120, v121
	v_add_f32_e32 v253, v253, v113
	s_waitcnt lgkmcnt(8)
	v_mfma_f32_32x32x16_bf16 v[32:47], v[244:247], v[214:217], v[32:47]
	ds_read_b64_tr_b16 v[214:215], v3 offset:15552
	ds_read_b64_tr_b16 v[216:217], v3 offset:18112
	v_exp_f32_e32 v126, v126
	v_exp_f32_e32 v127, v127
	v_cvt_pk_bf16_f32 v249, v122, v123
	v_add_f32_e32 v254, v254, v114
	v_add_f32_e32 v213, v213, v115
	s_waitcnt lgkmcnt(8)
	v_mfma_f32_32x32x16_bf16 v[16:31], v[244:247], v[218:221], v[16:31]
	v_cvt_pk_bf16_f32 v250, v124, v125
	v_add_f32_e32 v252, v252, v116
	v_cvt_pk_bf16_f32 v251, v126, v127
	v_add_f32_e32 v253, v253, v117
	v_add_f32_e32 v254, v254, v118
	v_add_f32_e32 v213, v213, v119
	s_waitcnt lgkmcnt(6)
	v_mfma_f32_32x32x16_bf16 v[64:79], v[248:251], v[222:225], v[64:79]
	v_add_f32_e32 v252, v252, v120
	v_add_f32_e32 v253, v253, v121
	v_add_f32_e32 v254, v254, v122
	s_waitcnt lgkmcnt(4)
	v_mfma_f32_32x32x16_bf16 v[48:63], v[248:251], v[226:229], v[48:63]
	v_add_f32_e32 v213, v213, v123
	v_add_f32_e32 v252, v252, v124
	v_add_f32_e32 v253, v253, v125
	s_waitcnt lgkmcnt(2)
	v_mfma_f32_32x32x16_bf16 v[32:47], v[248:251], v[230:233], v[32:47]
	v_add_f32_e32 v254, v254, v126
	v_add_f32_e32 v213, v213, v127
	v_add_f32_e32 v252, v252, v253
	v_add_f32_e32 v254, v254, v213
	s_waitcnt lgkmcnt(0)
	v_mfma_f32_32x32x16_bf16 v[16:31], v[248:251], v[214:217], v[16:31]
	v_add_f32_e32 v252, v252, v254
	v_add_f32_e32 v2, v2, v252
	s_setprio 0
